# MO8+TRIM+IL+ROT2b+Z0b (loop-edge SALU block one LDS-DMA load earlier in the previous load segment)
# baseline (speedup 1.0000x reference)
.Lz0_0_1_ret:
	s_add_i32 s49, 0, 0x18000
	s_add_i32 s50, 0, 0x1c000
	v_add_u32_e32 v156, s49, v145
	v_add_u32_e32 v175, s50, v145
	ds_read_b128 v[140:143], v156
	ds_read_b128 v[148:151], v156 offset:1024
	ds_read_b128 v[152:155], v156 offset:2048
	ds_read_b128 v[156:159], v156 offset:3072
	ds_read_b128 v[160:163], v175
	ds_read_b128 v[164:167], v175 offset:1024
	ds_read_b128 v[168:171], v175 offset:2048
	ds_read_b128 v[190:193], v175 offset:3072
	s_add_u32 s24, s24, 0x100000
	s_addc_u32 s25, s25, 0
	s_mov_b32 m0, s37
	v_lshl_add_u64 v[244:245], s[24:25], 0, v[134:135]
	ds_read_b128 v[194:197], v147 offset:32768
	ds_read_b128 v[198:201], v147 offset:33792
	ds_read_b128 v[202:205], v147 offset:34816
	ds_read_b128 v[206:209], v147 offset:35840
	ds_read_b128 v[228:231], v147 offset:36864
	ds_read_b128 v[232:235], v147 offset:37888
	ds_read_b128 v[236:239], v147 offset:38912
	ds_read_b128 v[240:243], v147 offset:39936
	global_load_lds_dwordx4 v[244:245], off
	v_lshl_add_u64 v[244:245], s[24:25], 0, v[132:133]
	s_mov_b32 m0, s38
	s_nop 0
	global_load_lds_dwordx4 v[244:245], off
	s_waitcnt vmcnt(8)
	s_waitcnt lgkmcnt(0)
	s_setprio 1
	s_barrier
	v_mfma_f32_16x16x32_bf16 v[126:129], v[140:143], v[194:197], v[126:129]
	v_mfma_f32_16x16x32_bf16 v[126:129], v[148:151], v[198:201], v[126:129]
	v_mfma_f32_16x16x32_bf16 v[118:121], v[148:151], v[206:209], v[118:121]
	v_mfma_f32_16x16x32_bf16 v[118:121], v[140:143], v[202:205], v[118:121]
	v_mfma_f32_16x16x32_bf16 v[102:105], v[140:143], v[228:231], v[102:105]
	v_mfma_f32_16x16x32_bf16 v[102:105], v[148:151], v[232:235], v[102:105]
	v_mfma_f32_16x16x32_bf16 v[86:89], v[148:151], v[240:243], v[86:89]
	v_mfma_f32_16x16x32_bf16 v[86:89], v[140:143], v[236:239], v[86:89]
	v_mfma_f32_16x16x32_bf16 v[78:81], v[152:155], v[236:239], v[78:81]
	v_mfma_f32_16x16x32_bf16 v[78:81], v[156:159], v[240:243], v[78:81]
	v_mfma_f32_16x16x32_bf16 v[94:97], v[156:159], v[232:235], v[94:97]
	v_mfma_f32_16x16x32_bf16 v[94:97], v[152:155], v[228:231], v[94:97]
	v_mfma_f32_16x16x32_bf16 v[110:113], v[152:155], v[202:205], v[110:113]
	v_mfma_f32_16x16x32_bf16 v[110:113], v[156:159], v[206:209], v[110:113]
	v_mfma_f32_16x16x32_bf16 v[122:125], v[156:159], v[198:201], v[122:125]
	v_mfma_f32_16x16x32_bf16 v[122:125], v[152:155], v[194:197], v[122:125]
	v_mfma_f32_16x16x32_bf16 v[114:117], v[160:163], v[194:197], v[114:117]
	v_mfma_f32_16x16x32_bf16 v[114:117], v[164:167], v[198:201], v[114:117]
	v_mfma_f32_16x16x32_bf16 v[98:101], v[164:167], v[206:209], v[98:101]
	v_mfma_f32_16x16x32_bf16 v[98:101], v[160:163], v[202:205], v[98:101]
	v_mfma_f32_16x16x32_bf16 v[82:85], v[160:163], v[228:231], v[82:85]
	v_mfma_f32_16x16x32_bf16 v[82:85], v[164:167], v[232:235], v[82:85]
	v_mfma_f32_16x16x32_bf16 v[70:73], v[164:167], v[240:243], v[70:73]
	v_mfma_f32_16x16x32_bf16 v[70:73], v[160:163], v[236:239], v[70:73]
	v_mfma_f32_16x16x32_bf16 v[66:69], v[168:171], v[236:239], v[66:69]
	v_mfma_f32_16x16x32_bf16 v[66:69], v[190:193], v[240:243], v[66:69]
	v_mfma_f32_16x16x32_bf16 v[74:77], v[190:193], v[232:235], v[74:77]
	v_mfma_f32_16x16x32_bf16 v[74:77], v[168:171], v[228:231], v[74:77]
	v_mfma_f32_16x16x32_bf16 v[90:93], v[168:171], v[202:205], v[90:93]
	v_mfma_f32_16x16x32_bf16 v[90:93], v[190:193], v[206:209], v[90:93]
	v_mfma_f32_16x16x32_bf16 v[106:109], v[190:193], v[198:201], v[106:109]
	v_mfma_f32_16x16x32_bf16 v[106:109], v[168:171], v[194:197], v[106:109]
	s_barrier
	s_setprio 0
	s_add_i32 s24, s49, s26
	v_lshl_add_u64 v[172:173], v[172:173], 0, s[34:35]
	s_mov_b32 m0, s24
	s_nop 0
	global_load_lds_dwordx4 v[172:173], off
	ds_read_b128 v[194:197], v147 offset:49152
	ds_read_b128 v[198:201], v147 offset:50176
	s_add_i32 m0, s24, 0x2000
	s_add_u32 s22, s22, 0x100080
	v_lshl_add_u64 v[172:173], v[178:179], 0, s[34:35]
	s_addc_u32 s23, s23, 0
	s_add_i32 s24, s50, s26
	global_load_lds_dwordx4 v[172:173], off
	ds_read_b128 v[202:205], v147 offset:51200
	ds_read_b128 v[206:209], v147 offset:52224
	v_lshl_add_u64 v[172:173], s[22:23], 0, v[0:1]
	s_mov_b32 m0, s24
	s_nop 0
	global_load_lds_dwordx4 v[172:173], off
	ds_read_b128 v[228:231], v147 offset:53248
	ds_read_b128 v[232:235], v147 offset:54272
	v_lshl_add_u64 v[172:173], s[22:23], 0, v[130:131]
	s_add_i32 m0, s24, 0x2000
	s_nop 0
	global_load_lds_dwordx4 v[172:173], off
	s_add_i32 s48, s48, 2
	s_add_u32 s18, s18, 0x100
	s_addc_u32 s19, s19, 0
	s_add_u32 s46, s46, 0x100
	s_addc_u32 s47, s47, 0
	s_add_u32 s22, s18, 0xfff00080
	s_addc_u32 s23, s19, -1
	s_cmp_eq_u32 s48, 60
	s_cselect_b32 s25, s9, s23
	s_cselect_b32 s24, s44, s22
	s_cselect_b32 s23, s7, s47
	s_cselect_b32 s22, s45, s46
	ds_read_b128 v[236:239], v147 offset:55296
	ds_read_b128 v[240:243], v147 offset:56320
	v_lshl_add_u64 v[172:173], v[180:181], 0, s[34:35]
	s_mov_b32 m0, s39
	s_nop 0
	global_load_lds_dwordx4 v[172:173], off
	v_lshl_add_u64 v[172:173], v[210:211], 0, s[34:35]
	s_mov_b32 m0, s40
	s_nop 0
	global_load_lds_dwordx4 v[172:173], off
	s_waitcnt vmcnt(8)
	s_waitcnt lgkmcnt(0)
	s_setprio 1
	s_barrier
	v_mfma_f32_16x16x32_bf16 v[62:65], v[140:143], v[194:197], v[62:65]
	v_mfma_f32_16x16x32_bf16 v[62:65], v[148:151], v[198:201], v[62:65]
	v_mfma_f32_16x16x32_bf16 v[54:57], v[148:151], v[206:209], v[54:57]
	v_mfma_f32_16x16x32_bf16 v[54:57], v[140:143], v[202:205], v[54:57]
	v_mfma_f32_16x16x32_bf16 v[38:41], v[140:143], v[228:231], v[38:41]
	v_mfma_f32_16x16x32_bf16 v[38:41], v[148:151], v[232:235], v[38:41]
	v_mfma_f32_16x16x32_bf16 v[22:25], v[148:151], v[240:243], v[22:25]
	v_mfma_f32_16x16x32_bf16 v[22:25], v[140:143], v[236:239], v[22:25]
	v_mfma_f32_16x16x32_bf16 v[14:17], v[152:155], v[236:239], v[14:17]
	v_mfma_f32_16x16x32_bf16 v[14:17], v[156:159], v[240:243], v[14:17]
	v_mfma_f32_16x16x32_bf16 v[30:33], v[156:159], v[232:235], v[30:33]
	v_mfma_f32_16x16x32_bf16 v[30:33], v[152:155], v[228:231], v[30:33]
	v_mfma_f32_16x16x32_bf16 v[46:49], v[152:155], v[202:205], v[46:49]
	v_mfma_f32_16x16x32_bf16 v[46:49], v[156:159], v[206:209], v[46:49]
	v_mfma_f32_16x16x32_bf16 v[58:61], v[156:159], v[198:201], v[58:61]
	v_mfma_f32_16x16x32_bf16 v[58:61], v[152:155], v[194:197], v[58:61]
	v_mfma_f32_16x16x32_bf16 v[50:53], v[160:163], v[194:197], v[50:53]
	v_mfma_f32_16x16x32_bf16 v[50:53], v[164:167], v[198:201], v[50:53]
	v_mfma_f32_16x16x32_bf16 v[34:37], v[164:167], v[206:209], v[34:37]
	v_mfma_f32_16x16x32_bf16 v[34:37], v[160:163], v[202:205], v[34:37]
	v_mfma_f32_16x16x32_bf16 v[18:21], v[160:163], v[228:231], v[18:21]
	v_mfma_f32_16x16x32_bf16 v[18:21], v[164:167], v[232:235], v[18:21]
	v_mfma_f32_16x16x32_bf16 v[6:9], v[164:167], v[240:243], v[6:9]
	v_mfma_f32_16x16x32_bf16 v[6:9], v[160:163], v[236:239], v[6:9]
	v_mfma_f32_16x16x32_bf16 v[2:5], v[168:171], v[236:239], v[2:5]
	v_mfma_f32_16x16x32_bf16 v[2:5], v[190:193], v[240:243], v[2:5]
	v_mfma_f32_16x16x32_bf16 v[10:13], v[190:193], v[232:235], v[10:13]
	v_mfma_f32_16x16x32_bf16 v[10:13], v[168:171], v[228:231], v[10:13]
	v_mfma_f32_16x16x32_bf16 v[26:29], v[168:171], v[202:205], v[26:29]
	v_mfma_f32_16x16x32_bf16 v[26:29], v[190:193], v[206:209], v[26:29]
	v_mfma_f32_16x16x32_bf16 v[42:45], v[190:193], v[198:201], v[42:45]
	v_mfma_f32_16x16x32_bf16 v[42:45], v[168:171], v[194:197], v[42:45]
	s_barrier
	s_setprio 0
	s_cmp_gt_u32 s48, 61
	s_cbranch_scc0 .LBB0_139
	s_and_b64 vcc, exec, s[4:5]
	s_cbranch_vccz .LBB0_142
	s_barrier

.Lz0_1_1_ret:
	s_add_i32 s53, 0, 0x18000
	s_add_i32 s54, 0, 0x1c000
	v_add_u32_e32 v158, s53, v143
	v_add_u32_e32 v175, s54, v143
	ds_read_b128 v[146:149], v158
	ds_read_b128 v[150:153], v158 offset:1024
	ds_read_b128 v[154:157], v158 offset:2048
	ds_read_b128 v[158:161], v158 offset:3072
	ds_read_b128 v[162:165], v175
	ds_read_b128 v[166:169], v175 offset:1024
	ds_read_b128 v[170:173], v175 offset:2048
	ds_read_b128 v[178:181], v175 offset:3072
	s_add_u32 s24, s24, 0x100000
	s_addc_u32 s25, s25, 0
	s_mov_b32 m0, s41
	v_lshl_add_u64 v[226:227], s[24:25], 0, v[134:135]
	ds_read_b128 v[190:193], v145 offset:32768
	ds_read_b128 v[194:197], v145 offset:33792
	ds_read_b128 v[198:201], v145 offset:34816
	ds_read_b128 v[202:205], v145 offset:35840
	ds_read_b128 v[206:209], v145 offset:36864
	ds_read_b128 v[228:231], v145 offset:37888
	ds_read_b128 v[232:235], v145 offset:38912
	ds_read_b128 v[236:239], v145 offset:39936
	global_load_lds_dwordx4 v[226:227], off
	v_lshl_add_u64 v[226:227], s[24:25], 0, v[132:133]
	s_mov_b32 m0, s42
	s_nop 0
	global_load_lds_dwordx4 v[226:227], off
	s_waitcnt vmcnt(8)
	s_waitcnt lgkmcnt(0)
	s_setprio 1
	s_barrier
	v_mfma_f32_16x16x32_bf16 v[126:129], v[146:149], v[190:193], v[126:129]
	v_mfma_f32_16x16x32_bf16 v[126:129], v[150:153], v[194:197], v[126:129]
	v_mfma_f32_16x16x32_bf16 v[118:121], v[150:153], v[202:205], v[118:121]
	v_mfma_f32_16x16x32_bf16 v[118:121], v[146:149], v[198:201], v[118:121]
	v_mfma_f32_16x16x32_bf16 v[102:105], v[146:149], v[206:209], v[102:105]
	v_mfma_f32_16x16x32_bf16 v[102:105], v[150:153], v[228:231], v[102:105]
	v_mfma_f32_16x16x32_bf16 v[86:89], v[150:153], v[236:239], v[86:89]
	v_mfma_f32_16x16x32_bf16 v[86:89], v[146:149], v[232:235], v[86:89]
	v_mfma_f32_16x16x32_bf16 v[78:81], v[154:157], v[232:235], v[78:81]
	v_mfma_f32_16x16x32_bf16 v[78:81], v[158:161], v[236:239], v[78:81]
	v_mfma_f32_16x16x32_bf16 v[94:97], v[158:161], v[228:231], v[94:97]
	v_mfma_f32_16x16x32_bf16 v[94:97], v[154:157], v[206:209], v[94:97]
	v_mfma_f32_16x16x32_bf16 v[110:113], v[154:157], v[198:201], v[110:113]
	v_mfma_f32_16x16x32_bf16 v[110:113], v[158:161], v[202:205], v[110:113]
	v_mfma_f32_16x16x32_bf16 v[122:125], v[158:161], v[194:197], v[122:125]
	v_mfma_f32_16x16x32_bf16 v[122:125], v[154:157], v[190:193], v[122:125]
	v_mfma_f32_16x16x32_bf16 v[114:117], v[162:165], v[190:193], v[114:117]
	v_mfma_f32_16x16x32_bf16 v[114:117], v[166:169], v[194:197], v[114:117]
	v_mfma_f32_16x16x32_bf16 v[98:101], v[166:169], v[202:205], v[98:101]
	v_mfma_f32_16x16x32_bf16 v[98:101], v[162:165], v[198:201], v[98:101]
	v_mfma_f32_16x16x32_bf16 v[82:85], v[162:165], v[206:209], v[82:85]
	v_mfma_f32_16x16x32_bf16 v[82:85], v[166:169], v[228:231], v[82:85]
	v_mfma_f32_16x16x32_bf16 v[70:73], v[166:169], v[236:239], v[70:73]
	v_mfma_f32_16x16x32_bf16 v[70:73], v[162:165], v[232:235], v[70:73]
	v_mfma_f32_16x16x32_bf16 v[66:69], v[170:173], v[232:235], v[66:69]
	v_mfma_f32_16x16x32_bf16 v[66:69], v[178:181], v[236:239], v[66:69]
	v_mfma_f32_16x16x32_bf16 v[74:77], v[178:181], v[228:231], v[74:77]
	v_mfma_f32_16x16x32_bf16 v[74:77], v[170:173], v[206:209], v[74:77]
	v_mfma_f32_16x16x32_bf16 v[90:93], v[170:173], v[198:201], v[90:93]
	v_mfma_f32_16x16x32_bf16 v[90:93], v[178:181], v[202:205], v[90:93]
	v_mfma_f32_16x16x32_bf16 v[106:109], v[178:181], v[194:197], v[106:109]
	v_mfma_f32_16x16x32_bf16 v[106:109], v[170:173], v[190:193], v[106:109]
	s_barrier
	s_setprio 0
	s_add_i32 s24, s53, s38
	v_lshl_add_u64 v[140:141], v[140:141], 0, s[34:35]
	s_mov_b32 m0, s24
	s_nop 0
	global_load_lds_dwordx4 v[140:141], off
	ds_read_b128 v[190:193], v145 offset:49152
	ds_read_b128 v[194:197], v145 offset:50176
	s_add_i32 m0, s24, 0x2000
	s_add_u32 s22, s22, 0x100080
	v_lshl_add_u64 v[140:141], v[186:187], 0, s[34:35]
	s_addc_u32 s23, s23, 0
	s_add_i32 s24, s54, s38
	global_load_lds_dwordx4 v[140:141], off
	ds_read_b128 v[198:201], v145 offset:51200
	ds_read_b128 v[202:205], v145 offset:52224
	v_lshl_add_u64 v[140:141], s[22:23], 0, v[0:1]
	s_mov_b32 m0, s24
	s_nop 0
	global_load_lds_dwordx4 v[140:141], off
	ds_read_b128 v[206:209], v145 offset:53248
	ds_read_b128 v[228:231], v145 offset:54272
	v_lshl_add_u64 v[140:141], s[22:23], 0, v[130:131]
	s_add_i32 m0, s24, 0x2000
	s_nop 0
	global_load_lds_dwordx4 v[140:141], off
	s_add_i32 s52, s52, 2
	s_add_u32 s18, s18, 0x100
	s_addc_u32 s19, s19, 0
	s_add_u32 s50, s50, 0x100
	s_addc_u32 s51, s51, 0
	s_add_u32 s22, s18, 0xfff00080
	s_addc_u32 s23, s19, -1
	s_cmp_eq_u32 s52, 60
	s_cselect_b32 s25, s9, s23
	s_cselect_b32 s24, s48, s22
	s_cselect_b32 s23, s7, s51
	s_cselect_b32 s22, s49, s50
	ds_read_b128 v[232:235], v145 offset:55296
	ds_read_b128 v[236:239], v145 offset:56320
	v_lshl_add_u64 v[140:141], v[188:189], 0, s[34:35]
	s_mov_b32 m0, s43
	s_nop 0
	global_load_lds_dwordx4 v[140:141], off
	v_lshl_add_u64 v[140:141], v[210:211], 0, s[34:35]
	s_mov_b32 m0, s44
	s_nop 0
	global_load_lds_dwordx4 v[140:141], off
	s_waitcnt vmcnt(8)
	s_waitcnt lgkmcnt(0)
	s_setprio 1
	s_barrier
	v_mfma_f32_16x16x32_bf16 v[62:65], v[146:149], v[190:193], v[62:65]
	v_mfma_f32_16x16x32_bf16 v[62:65], v[150:153], v[194:197], v[62:65]
	v_mfma_f32_16x16x32_bf16 v[54:57], v[150:153], v[202:205], v[54:57]
	v_mfma_f32_16x16x32_bf16 v[54:57], v[146:149], v[198:201], v[54:57]
	v_mfma_f32_16x16x32_bf16 v[38:41], v[146:149], v[206:209], v[38:41]
	v_mfma_f32_16x16x32_bf16 v[38:41], v[150:153], v[228:231], v[38:41]
	v_mfma_f32_16x16x32_bf16 v[22:25], v[150:153], v[236:239], v[22:25]
	v_mfma_f32_16x16x32_bf16 v[22:25], v[146:149], v[232:235], v[22:25]
	v_mfma_f32_16x16x32_bf16 v[14:17], v[154:157], v[232:235], v[14:17]
	v_mfma_f32_16x16x32_bf16 v[14:17], v[158:161], v[236:239], v[14:17]
	v_mfma_f32_16x16x32_bf16 v[30:33], v[158:161], v[228:231], v[30:33]
	v_mfma_f32_16x16x32_bf16 v[30:33], v[154:157], v[206:209], v[30:33]
	v_mfma_f32_16x16x32_bf16 v[46:49], v[154:157], v[198:201], v[46:49]
	v_mfma_f32_16x16x32_bf16 v[46:49], v[158:161], v[202:205], v[46:49]
	v_mfma_f32_16x16x32_bf16 v[58:61], v[158:161], v[194:197], v[58:61]
	v_mfma_f32_16x16x32_bf16 v[58:61], v[154:157], v[190:193], v[58:61]
	v_mfma_f32_16x16x32_bf16 v[50:53], v[162:165], v[190:193], v[50:53]
	v_mfma_f32_16x16x32_bf16 v[50:53], v[166:169], v[194:197], v[50:53]
	v_mfma_f32_16x16x32_bf16 v[34:37], v[166:169], v[202:205], v[34:37]
	v_mfma_f32_16x16x32_bf16 v[34:37], v[162:165], v[198:201], v[34:37]
	v_mfma_f32_16x16x32_bf16 v[18:21], v[162:165], v[206:209], v[18:21]
	v_mfma_f32_16x16x32_bf16 v[18:21], v[166:169], v[228:231], v[18:21]
	v_mfma_f32_16x16x32_bf16 v[6:9], v[166:169], v[236:239], v[6:9]
	v_mfma_f32_16x16x32_bf16 v[6:9], v[162:165], v[232:235], v[6:9]
	v_mfma_f32_16x16x32_bf16 v[2:5], v[170:173], v[232:235], v[2:5]
	v_mfma_f32_16x16x32_bf16 v[2:5], v[178:181], v[236:239], v[2:5]
	v_mfma_f32_16x16x32_bf16 v[10:13], v[178:181], v[228:231], v[10:13]
	v_mfma_f32_16x16x32_bf16 v[10:13], v[170:173], v[206:209], v[10:13]
	v_mfma_f32_16x16x32_bf16 v[26:29], v[170:173], v[198:201], v[26:29]
	v_mfma_f32_16x16x32_bf16 v[26:29], v[178:181], v[202:205], v[26:29]
	v_mfma_f32_16x16x32_bf16 v[42:45], v[178:181], v[194:197], v[42:45]
	v_mfma_f32_16x16x32_bf16 v[42:45], v[170:173], v[190:193], v[42:45]
	s_barrier
	s_setprio 0
	s_cmp_gt_u32 s52, 61
	s_cbranch_scc0 .LBB0_575
	s_and_b64 vcc, exec, s[4:5]
	s_cbranch_vccz .LBB0_578
	s_barrier

.Lz0_2_1_ret:
	s_add_i32 s53, 0, 0x18000
	s_add_i32 s54, 0, 0x1c000
	v_add_u32_e32 v158, s53, v143
	v_add_u32_e32 v175, s54, v143
	ds_read_b128 v[146:149], v158
	ds_read_b128 v[150:153], v158 offset:1024
	ds_read_b128 v[154:157], v158 offset:2048
	ds_read_b128 v[158:161], v158 offset:3072
	ds_read_b128 v[162:165], v175
	ds_read_b128 v[166:169], v175 offset:1024
	ds_read_b128 v[170:173], v175 offset:2048
	ds_read_b128 v[178:181], v175 offset:3072
	s_add_u32 s22, s22, 0x100000
	s_addc_u32 s23, s23, 0
	s_mov_b32 m0, s41
	v_lshl_add_u64 v[226:227], s[22:23], 0, v[134:135]
	ds_read_b128 v[190:193], v145 offset:32768
	ds_read_b128 v[194:197], v145 offset:33792
	ds_read_b128 v[198:201], v145 offset:34816
	ds_read_b128 v[202:205], v145 offset:35840
	ds_read_b128 v[206:209], v145 offset:36864
	ds_read_b128 v[228:231], v145 offset:37888
	ds_read_b128 v[232:235], v145 offset:38912
	ds_read_b128 v[236:239], v145 offset:39936
	global_load_lds_dwordx4 v[226:227], off
	v_lshl_add_u64 v[226:227], s[22:23], 0, v[132:133]
	s_mov_b32 m0, s42
	s_nop 0
	global_load_lds_dwordx4 v[226:227], off
	s_waitcnt vmcnt(8)
	s_waitcnt lgkmcnt(0)
	s_setprio 1
	s_barrier
	v_mfma_f32_16x16x32_bf16 v[126:129], v[146:149], v[190:193], v[126:129]
	v_mfma_f32_16x16x32_bf16 v[126:129], v[150:153], v[194:197], v[126:129]
	v_mfma_f32_16x16x32_bf16 v[110:113], v[150:153], v[202:205], v[110:113]
	v_mfma_f32_16x16x32_bf16 v[110:113], v[146:149], v[198:201], v[110:113]
	v_mfma_f32_16x16x32_bf16 v[94:97], v[146:149], v[206:209], v[94:97]
	v_mfma_f32_16x16x32_bf16 v[94:97], v[150:153], v[228:231], v[94:97]
	v_mfma_f32_16x16x32_bf16 v[78:81], v[150:153], v[236:239], v[78:81]
	v_mfma_f32_16x16x32_bf16 v[78:81], v[146:149], v[232:235], v[78:81]
	v_mfma_f32_16x16x32_bf16 v[70:73], v[154:157], v[232:235], v[70:73]
	v_mfma_f32_16x16x32_bf16 v[70:73], v[158:161], v[236:239], v[70:73]
	v_mfma_f32_16x16x32_bf16 v[86:89], v[158:161], v[228:231], v[86:89]
	v_mfma_f32_16x16x32_bf16 v[86:89], v[154:157], v[206:209], v[86:89]
	v_mfma_f32_16x16x32_bf16 v[102:105], v[154:157], v[198:201], v[102:105]
	v_mfma_f32_16x16x32_bf16 v[102:105], v[158:161], v[202:205], v[102:105]
	v_mfma_f32_16x16x32_bf16 v[118:121], v[158:161], v[194:197], v[118:121]
	v_mfma_f32_16x16x32_bf16 v[118:121], v[154:157], v[190:193], v[118:121]
	v_mfma_f32_16x16x32_bf16 v[122:125], v[162:165], v[190:193], v[122:125]
	v_mfma_f32_16x16x32_bf16 v[122:125], v[166:169], v[194:197], v[122:125]
	v_mfma_f32_16x16x32_bf16 v[106:109], v[166:169], v[202:205], v[106:109]
	v_mfma_f32_16x16x32_bf16 v[106:109], v[162:165], v[198:201], v[106:109]
	v_mfma_f32_16x16x32_bf16 v[90:93], v[162:165], v[206:209], v[90:93]
	v_mfma_f32_16x16x32_bf16 v[90:93], v[166:169], v[228:231], v[90:93]
	v_mfma_f32_16x16x32_bf16 v[74:77], v[166:169], v[236:239], v[74:77]
	v_mfma_f32_16x16x32_bf16 v[74:77], v[162:165], v[232:235], v[74:77]
	v_mfma_f32_16x16x32_bf16 v[66:69], v[170:173], v[232:235], v[66:69]
	v_mfma_f32_16x16x32_bf16 v[66:69], v[178:181], v[236:239], v[66:69]
	v_mfma_f32_16x16x32_bf16 v[82:85], v[178:181], v[228:231], v[82:85]
	v_mfma_f32_16x16x32_bf16 v[82:85], v[170:173], v[206:209], v[82:85]
	v_mfma_f32_16x16x32_bf16 v[98:101], v[170:173], v[198:201], v[98:101]
	v_mfma_f32_16x16x32_bf16 v[98:101], v[178:181], v[202:205], v[98:101]
	v_mfma_f32_16x16x32_bf16 v[114:117], v[178:181], v[194:197], v[114:117]
	v_mfma_f32_16x16x32_bf16 v[114:117], v[170:173], v[190:193], v[114:117]
	s_barrier
	s_setprio 0
	s_add_i32 s22, s53, s26
	v_lshl_add_u64 v[140:141], v[140:141], 0, s[34:35]
	s_mov_b32 m0, s22
	s_nop 0
	global_load_lds_dwordx4 v[140:141], off
	ds_read_b128 v[190:193], v145 offset:49152
	ds_read_b128 v[194:197], v145 offset:50176
	s_add_i32 m0, s22, 0x2000
	s_add_u32 s18, s18, 0x100080
	v_lshl_add_u64 v[140:141], v[186:187], 0, s[34:35]
	s_addc_u32 s19, s19, 0
	s_add_i32 s22, s54, s26
	global_load_lds_dwordx4 v[140:141], off
	ds_read_b128 v[198:201], v145 offset:51200
	ds_read_b128 v[202:205], v145 offset:52224
	v_lshl_add_u64 v[140:141], s[18:19], 0, v[0:1]
	s_mov_b32 m0, s22
	s_nop 0
	global_load_lds_dwordx4 v[140:141], off
	ds_read_b128 v[206:209], v145 offset:53248
	ds_read_b128 v[228:231], v145 offset:54272
	v_lshl_add_u64 v[140:141], s[18:19], 0, v[130:131]
	s_add_i32 m0, s22, 0x2000
	s_nop 0
	global_load_lds_dwordx4 v[140:141], off
	s_add_i32 s52, s52, 2
	s_add_u32 s16, s16, 0x100
	s_addc_u32 s17, s17, 0
	s_add_u32 s50, s50, 0x100
	s_addc_u32 s51, s51, 0
	s_add_u32 s18, s16, 0xfff00080
	s_addc_u32 s19, s17, -1
	s_cmp_eq_u32 s52, 60
	s_cselect_b32 s23, s7, s19
	s_cselect_b32 s22, s48, s18
	s_cselect_b32 s19, s5, s51
	s_cselect_b32 s18, s49, s50
	ds_read_b128 v[232:235], v145 offset:55296
	ds_read_b128 v[236:239], v145 offset:56320
	v_lshl_add_u64 v[140:141], v[188:189], 0, s[34:35]
	s_mov_b32 m0, s43
	s_nop 0
	global_load_lds_dwordx4 v[140:141], off
	v_lshl_add_u64 v[140:141], v[210:211], 0, s[34:35]
	s_mov_b32 m0, s44
	s_nop 0
	global_load_lds_dwordx4 v[140:141], off
	s_waitcnt vmcnt(8)
	s_waitcnt lgkmcnt(0)
	s_setprio 1
	s_barrier
	v_mfma_f32_16x16x32_bf16 v[62:65], v[146:149], v[190:193], v[62:65]
	v_mfma_f32_16x16x32_bf16 v[62:65], v[150:153], v[194:197], v[62:65]
	v_mfma_f32_16x16x32_bf16 v[46:49], v[150:153], v[202:205], v[46:49]
	v_mfma_f32_16x16x32_bf16 v[46:49], v[146:149], v[198:201], v[46:49]
	v_mfma_f32_16x16x32_bf16 v[30:33], v[146:149], v[206:209], v[30:33]
	v_mfma_f32_16x16x32_bf16 v[30:33], v[150:153], v[228:231], v[30:33]
	v_mfma_f32_16x16x32_bf16 v[14:17], v[150:153], v[236:239], v[14:17]
	v_mfma_f32_16x16x32_bf16 v[14:17], v[146:149], v[232:235], v[14:17]
	v_mfma_f32_16x16x32_bf16 v[6:9], v[154:157], v[232:235], v[6:9]
	v_mfma_f32_16x16x32_bf16 v[6:9], v[158:161], v[236:239], v[6:9]
	v_mfma_f32_16x16x32_bf16 v[22:25], v[158:161], v[228:231], v[22:25]
	v_mfma_f32_16x16x32_bf16 v[22:25], v[154:157], v[206:209], v[22:25]
	v_mfma_f32_16x16x32_bf16 v[38:41], v[154:157], v[198:201], v[38:41]
	v_mfma_f32_16x16x32_bf16 v[38:41], v[158:161], v[202:205], v[38:41]
	v_mfma_f32_16x16x32_bf16 v[54:57], v[158:161], v[194:197], v[54:57]
	v_mfma_f32_16x16x32_bf16 v[54:57], v[154:157], v[190:193], v[54:57]
	v_mfma_f32_16x16x32_bf16 v[58:61], v[162:165], v[190:193], v[58:61]
	v_mfma_f32_16x16x32_bf16 v[58:61], v[166:169], v[194:197], v[58:61]
	v_mfma_f32_16x16x32_bf16 v[42:45], v[166:169], v[202:205], v[42:45]
	v_mfma_f32_16x16x32_bf16 v[42:45], v[162:165], v[198:201], v[42:45]
	v_mfma_f32_16x16x32_bf16 v[26:29], v[162:165], v[206:209], v[26:29]
	v_mfma_f32_16x16x32_bf16 v[26:29], v[166:169], v[228:231], v[26:29]
	v_mfma_f32_16x16x32_bf16 v[10:13], v[166:169], v[236:239], v[10:13]
	v_mfma_f32_16x16x32_bf16 v[10:13], v[162:165], v[232:235], v[10:13]
	v_mfma_f32_16x16x32_bf16 v[2:5], v[170:173], v[232:235], v[2:5]
	v_mfma_f32_16x16x32_bf16 v[2:5], v[178:181], v[236:239], v[2:5]
	v_mfma_f32_16x16x32_bf16 v[18:21], v[178:181], v[228:231], v[18:21]
	v_mfma_f32_16x16x32_bf16 v[18:21], v[170:173], v[206:209], v[18:21]
	v_mfma_f32_16x16x32_bf16 v[34:37], v[170:173], v[198:201], v[34:37]
	v_mfma_f32_16x16x32_bf16 v[34:37], v[178:181], v[202:205], v[34:37]
	v_mfma_f32_16x16x32_bf16 v[50:53], v[178:181], v[194:197], v[50:53]
	v_mfma_f32_16x16x32_bf16 v[50:53], v[170:173], v[190:193], v[50:53]
	s_barrier
	s_setprio 0
	s_cmp_gt_u32 s52, 61
	s_cbranch_scc0 .LBB0_721
	s_and_b64 vcc, exec, s[2:3]
	s_cbranch_vccz .LBB0_724
	s_barrier

.Lz0_3_1_ret:
	s_add_i32 s49, 0, 0x18000
	s_add_i32 s50, 0, 0x1c000
	v_add_u32_e32 v158, s49, v143
	v_add_u32_e32 v175, s50, v143
	ds_read_b128 v[146:149], v158
	ds_read_b128 v[150:153], v158 offset:1024
	ds_read_b128 v[154:157], v158 offset:2048
	ds_read_b128 v[158:161], v158 offset:3072
	ds_read_b128 v[162:165], v175
	ds_read_b128 v[166:169], v175 offset:1024
	ds_read_b128 v[170:173], v175 offset:2048
	ds_read_b128 v[178:181], v175 offset:3072
	s_add_u32 s14, s22, 0x2b0000
	s_addc_u32 s15, s23, 0
	s_mov_b32 m0, s37
	v_lshl_add_u64 v[226:227], s[14:15], 0, v[134:135]
	ds_read_b128 v[190:193], v145 offset:32768
	ds_read_b128 v[194:197], v145 offset:33792
	ds_read_b128 v[198:201], v145 offset:34816
	ds_read_b128 v[202:205], v145 offset:35840
	ds_read_b128 v[206:209], v145 offset:36864
	ds_read_b128 v[228:231], v145 offset:37888
	ds_read_b128 v[232:235], v145 offset:38912
	ds_read_b128 v[236:239], v145 offset:39936
	global_load_lds_dwordx4 v[226:227], off
	v_lshl_add_u64 v[226:227], s[14:15], 0, v[132:133]
	s_mov_b32 m0, s38
	s_nop 0
	global_load_lds_dwordx4 v[226:227], off
	s_waitcnt vmcnt(8)
	s_waitcnt lgkmcnt(0)
	s_setprio 1
	s_barrier
	v_mfma_f32_16x16x32_bf16 v[126:129], v[146:149], v[190:193], v[126:129]
	v_mfma_f32_16x16x32_bf16 v[126:129], v[150:153], v[194:197], v[126:129]
	v_mfma_f32_16x16x32_bf16 v[118:121], v[150:153], v[202:205], v[118:121]
	v_mfma_f32_16x16x32_bf16 v[118:121], v[146:149], v[198:201], v[118:121]
	v_mfma_f32_16x16x32_bf16 v[102:105], v[146:149], v[206:209], v[102:105]
	v_mfma_f32_16x16x32_bf16 v[102:105], v[150:153], v[228:231], v[102:105]
	v_mfma_f32_16x16x32_bf16 v[86:89], v[150:153], v[236:239], v[86:89]
	v_mfma_f32_16x16x32_bf16 v[86:89], v[146:149], v[232:235], v[86:89]
	v_mfma_f32_16x16x32_bf16 v[78:81], v[154:157], v[232:235], v[78:81]
	v_mfma_f32_16x16x32_bf16 v[78:81], v[158:161], v[236:239], v[78:81]
	v_mfma_f32_16x16x32_bf16 v[94:97], v[158:161], v[228:231], v[94:97]
	v_mfma_f32_16x16x32_bf16 v[94:97], v[154:157], v[206:209], v[94:97]
	v_mfma_f32_16x16x32_bf16 v[110:113], v[154:157], v[198:201], v[110:113]
	v_mfma_f32_16x16x32_bf16 v[110:113], v[158:161], v[202:205], v[110:113]
	v_mfma_f32_16x16x32_bf16 v[122:125], v[158:161], v[194:197], v[122:125]
	v_mfma_f32_16x16x32_bf16 v[122:125], v[154:157], v[190:193], v[122:125]
	v_mfma_f32_16x16x32_bf16 v[114:117], v[162:165], v[190:193], v[114:117]
	v_mfma_f32_16x16x32_bf16 v[114:117], v[166:169], v[194:197], v[114:117]
	v_mfma_f32_16x16x32_bf16 v[98:101], v[166:169], v[202:205], v[98:101]
	v_mfma_f32_16x16x32_bf16 v[98:101], v[162:165], v[198:201], v[98:101]
	v_mfma_f32_16x16x32_bf16 v[82:85], v[162:165], v[206:209], v[82:85]
	v_mfma_f32_16x16x32_bf16 v[82:85], v[166:169], v[228:231], v[82:85]
	v_mfma_f32_16x16x32_bf16 v[70:73], v[166:169], v[236:239], v[70:73]
	v_mfma_f32_16x16x32_bf16 v[70:73], v[162:165], v[232:235], v[70:73]
	v_mfma_f32_16x16x32_bf16 v[66:69], v[170:173], v[232:235], v[66:69]
	v_mfma_f32_16x16x32_bf16 v[66:69], v[178:181], v[236:239], v[66:69]
	v_mfma_f32_16x16x32_bf16 v[74:77], v[178:181], v[228:231], v[74:77]
	v_mfma_f32_16x16x32_bf16 v[74:77], v[170:173], v[206:209], v[74:77]
	v_mfma_f32_16x16x32_bf16 v[90:93], v[170:173], v[198:201], v[90:93]
	v_mfma_f32_16x16x32_bf16 v[90:93], v[178:181], v[202:205], v[90:93]
	v_mfma_f32_16x16x32_bf16 v[106:109], v[178:181], v[194:197], v[106:109]
	v_mfma_f32_16x16x32_bf16 v[106:109], v[170:173], v[190:193], v[106:109]
	s_barrier
	s_setprio 0
	s_add_i32 s14, s49, s26
	v_lshl_add_u64 v[140:141], v[140:141], 0, s[34:35]
	s_mov_b32 m0, s14
	s_nop 0
	global_load_lds_dwordx4 v[140:141], off
	ds_read_b128 v[190:193], v145 offset:49152
	ds_read_b128 v[194:197], v145 offset:50176
	s_add_i32 m0, s14, 0x2000
	s_add_u32 s14, s18, 0x2b0080
	v_lshl_add_u64 v[140:141], v[186:187], 0, s[34:35]
	s_addc_u32 s15, s19, 0
	s_add_i32 s18, s50, s26
	global_load_lds_dwordx4 v[140:141], off
	ds_read_b128 v[198:201], v145 offset:51200
	ds_read_b128 v[202:205], v145 offset:52224
	v_lshl_add_u64 v[140:141], s[14:15], 0, v[0:1]
	s_mov_b32 m0, s18
	s_nop 0
	global_load_lds_dwordx4 v[140:141], off
	ds_read_b128 v[206:209], v145 offset:53248
	ds_read_b128 v[228:231], v145 offset:54272
	v_lshl_add_u64 v[140:141], s[14:15], 0, v[130:131]
	s_add_i32 m0, s18, 0x2000
	s_nop 0
	global_load_lds_dwordx4 v[140:141], off
	s_add_i32 s48, s48, 2
	s_add_u32 s46, s46, 0x100
	s_addc_u32 s47, s47, 0
	s_mov_b64 s[14:15], s[16:17]
	s_add_u32 s16, s14, 0x100
	s_addc_u32 s17, s15, 0
	s_cmpk_eq_i32 s48, 0xa8
	s_cselect_b32 s23, s5, s17
	s_cselect_b32 s22, s4, s16
	s_cselect_b32 s19, s9, s47
	s_cselect_b32 s18, s8, s46
	ds_read_b128 v[232:235], v145 offset:55296
	ds_read_b128 v[236:239], v145 offset:56320
	v_lshl_add_u64 v[140:141], v[188:189], 0, s[34:35]
	s_mov_b32 m0, s39
	s_nop 0
	global_load_lds_dwordx4 v[140:141], off
	v_lshl_add_u64 v[140:141], v[210:211], 0, s[34:35]
	s_mov_b32 m0, s40
	s_nop 0
	global_load_lds_dwordx4 v[140:141], off
	s_waitcnt vmcnt(8)
	s_waitcnt lgkmcnt(0)
	s_setprio 1
	s_barrier
	v_mfma_f32_16x16x32_bf16 v[62:65], v[146:149], v[190:193], v[62:65]
	v_mfma_f32_16x16x32_bf16 v[62:65], v[150:153], v[194:197], v[62:65]
	v_mfma_f32_16x16x32_bf16 v[54:57], v[150:153], v[202:205], v[54:57]
	v_mfma_f32_16x16x32_bf16 v[54:57], v[146:149], v[198:201], v[54:57]
	v_mfma_f32_16x16x32_bf16 v[38:41], v[146:149], v[206:209], v[38:41]
	v_mfma_f32_16x16x32_bf16 v[38:41], v[150:153], v[228:231], v[38:41]
	v_mfma_f32_16x16x32_bf16 v[22:25], v[150:153], v[236:239], v[22:25]
	v_mfma_f32_16x16x32_bf16 v[22:25], v[146:149], v[232:235], v[22:25]
	v_mfma_f32_16x16x32_bf16 v[14:17], v[154:157], v[232:235], v[14:17]
	v_mfma_f32_16x16x32_bf16 v[14:17], v[158:161], v[236:239], v[14:17]
	v_mfma_f32_16x16x32_bf16 v[30:33], v[158:161], v[228:231], v[30:33]
	v_mfma_f32_16x16x32_bf16 v[30:33], v[154:157], v[206:209], v[30:33]
	v_mfma_f32_16x16x32_bf16 v[46:49], v[154:157], v[198:201], v[46:49]
	v_mfma_f32_16x16x32_bf16 v[46:49], v[158:161], v[202:205], v[46:49]
	v_mfma_f32_16x16x32_bf16 v[58:61], v[158:161], v[194:197], v[58:61]
	v_mfma_f32_16x16x32_bf16 v[58:61], v[154:157], v[190:193], v[58:61]
	v_mfma_f32_16x16x32_bf16 v[50:53], v[162:165], v[190:193], v[50:53]
	v_mfma_f32_16x16x32_bf16 v[50:53], v[166:169], v[194:197], v[50:53]
	v_mfma_f32_16x16x32_bf16 v[34:37], v[166:169], v[202:205], v[34:37]
	v_mfma_f32_16x16x32_bf16 v[34:37], v[162:165], v[198:201], v[34:37]
	v_mfma_f32_16x16x32_bf16 v[18:21], v[162:165], v[206:209], v[18:21]
	v_mfma_f32_16x16x32_bf16 v[18:21], v[166:169], v[228:231], v[18:21]
	v_mfma_f32_16x16x32_bf16 v[6:9], v[166:169], v[236:239], v[6:9]
	v_mfma_f32_16x16x32_bf16 v[6:9], v[162:165], v[232:235], v[6:9]
	v_mfma_f32_16x16x32_bf16 v[2:5], v[170:173], v[232:235], v[2:5]
	v_mfma_f32_16x16x32_bf16 v[2:5], v[178:181], v[236:239], v[2:5]
	v_mfma_f32_16x16x32_bf16 v[10:13], v[178:181], v[228:231], v[10:13]
	v_mfma_f32_16x16x32_bf16 v[10:13], v[170:173], v[206:209], v[10:13]
	v_mfma_f32_16x16x32_bf16 v[26:29], v[170:173], v[198:201], v[26:29]
	v_mfma_f32_16x16x32_bf16 v[26:29], v[178:181], v[202:205], v[26:29]
	v_mfma_f32_16x16x32_bf16 v[42:45], v[178:181], v[194:197], v[42:45]
	v_mfma_f32_16x16x32_bf16 v[42:45], v[170:173], v[190:193], v[42:45]
	s_barrier
	s_setprio 0
	s_cmpk_gt_u32 s48, 0xa9
	s_cbranch_scc0 .LBB0_805
	s_and_b64 vcc, exec, s[6:7]
	s_cbranch_vccz .LBB0_808
	s_barrier
